# v39 + out-/down-projection epilogues: cache prefetch of the second half's residual rows at the epilogue head
# baseline (speedup 1.0000x reference)
; __device__ __forceinline__ unsigned pk_f16(float lo, float hi) { f32x2 v = {lo, hi}; f16x2_t h = __builtin_convertvector(v, f16x2_t); return __builtin_bit_cast(unsigned, h); }
; __device__ __forceinline__ f32x2 up_f16(unsigned w) { return __builtin_convertvector(__builtin_bit_cast(f16x2_t, w), f32x2); }
;     __device__ __forceinline__ void operator()(const f32x4 (&acc)[2][2][4][2], const Unit& u, int wr, int wc, int fr, int fq) const {
;         const int row0 = u.pm * BM + wr * 64 + fr; const int b = (u.pm * BM) >> 14;
;         int fqo = fq; asm volatile("" : "+v"(fqo));
;         const int col0 = u.pn * BM + wc * 32 + 8 * fqo;
;         float ss[2][4];
; #pragma unroll
;         for (int ai = 0; ai < 2; ++ai)
; #pragma unroll
;             for (int m = 0; m < 4; ++m) ss[ai][m] = 0.f;
; #pragma unroll
;         for (int bj = 0; bj < 2; ++bj) {
;             f32x4 gv[2];
; #pragma unroll
;             for (int n = 0; n < 2; ++n) gv[n] = *(const f32x4*)(gate + (size_t)b * gstride + col0 + bj * HALF + 4 * n);
;             u32x4 pq[2][4];
; #pragma unroll
;             for (int ai = 0; ai < 2; ++ai)
; #pragma unroll
;                 for (int m = 0; m < 4; ++m) pq[ai][m] = *(const u32x4*)(base + (size_t)(row0 + ai * HALF + m * 16) * 1024 + col0 + bj * HALF);
;             asm volatile("" ::: "memory");
; #pragma unroll
;             for (int ai = 0; ai < 2; ++ai) {
; #pragma unroll
;                 for (int m = 0; m < 4; ++m) { const size_t off = (size_t)(row0 + ai * HALF + m * 16) * 1024 + col0 + bj * HALF;
;                     float rc = 1.0f; if constexpr (GN) rc = rsqrtf(gss[2 * 32768 + row0 + ai * HALF + m * 16] * (1.0f / 384.0f) + 1e-6f);
;                     const u32x4 q = pq[ai][m];
;                     const f32x2 qa_ = up_f16(q.x), qb_ = up_f16(q.y), qc_ = up_f16(q.z), qd_ = up_f16(q.w);
;                     const f32x4 x0 = (f32x4){qa_[0], qa_[1], qb_[0], qb_[1]} + gv[0] * (acc[ai][bj][m][0] * rc),
;                                 x1 = (f32x4){qc_[0], qc_[1], qd_[0], qd_[1]} + gv[1] * (acc[ai][bj][m][1] * rc);
;                     { u32x4 wx; wx.x = pk_f16(x0[0], x0[1]); wx.y = pk_f16(x0[2], x0[3]); wx.z = pk_f16(x1[0], x1[1]); wx.w = pk_f16(x1[2], x1[3]); *(u32x4*)(out + off) = wx; }
.LBB0_806:
	s_lshl_b32 s1, s68, 8
	v_mov_b32_e32 v128, v237
	s_ashr_i32 s0, s69, 6
	s_or_b32 s1, s1, s29
	v_or_b32_e32 v140, 16, v186
	v_lshl_add_u32 v138, v128, 3, s1
	s_mul_hi_i32 s1, s0, 0x6000
	s_mulk_i32 s0, 0x6000
	s_add_u32 s0, s20, s0
	v_ashrrev_i32_e32 v139, 31, v138
	s_addc_u32 s1, s21, s1
	v_ashrrev_i32_e32 v141, 31, v140
	v_lshlrev_b64 v[208:209], 11, v[186:187]
	v_lshl_add_u64 v[190:191], v[138:139], 2, s[0:1]
	v_lshlrev_b64 v[246:247], 11, v[140:141]
	v_or_b32_e32 v140, 32, v186
	s_mov_b64 s[0:1], 0x48000
	v_ashrrev_i32_e32 v141, 31, v140
	v_lshl_add_u64 v[220:221], v[208:209], 0, s[0:1]
	s_mov_b64 s[0:1], 0x50000
	s_mov_b64 s[4:5], 0x40000
	v_lshlrev_b64 v[206:207], 1, v[138:139]
	v_lshlrev_b64 v[248:249], 11, v[140:141]
	v_or_b32_e32 v140, 48, v186
	v_lshl_add_u64 v[222:223], v[208:209], 0, s[0:1]
	s_mov_b64 s[0:1], 0x58000
	v_lshl_add_u64 v[218:219], v[208:209], 0, s[4:5]
	v_lshl_add_u64 v[138:139], s[96:97], 0, v[206:207]
	v_ashrrev_i32_e32 v141, 31, v140
	v_lshl_add_u64 v[216:217], v[208:209], 0, s[0:1]
	s_mov_b32 s0, 0x40000
	v_lshl_add_u64 v[192:193], v[138:139], 0, v[208:209]
	v_lshl_add_u64 v[196:197], v[138:139], 0, v[248:249]
	v_lshlrev_b64 v[224:225], 11, v[140:141]
	v_lshl_add_u64 v[200:201], v[138:139], 0, v[218:219]
	v_lshl_add_u64 v[204:205], v[138:139], 0, v[222:223]
	v_add_co_u32_e32 v188, vcc, s0, v188
	global_load_dwordx4 v[130:133], v[190:191], off offset:16
	global_load_dwordx4 v[134:137], v[190:191], off
	v_lshl_add_u64 v[194:195], v[138:139], 0, v[246:247]
	global_load_dwordx4 v[212:215], v[192:193], off
	global_load_dwordx4 v[242:245], v[194:195], off
	v_lshl_add_u64 v[198:199], v[138:139], 0, v[224:225]
	global_load_dwordx4 v[158:161], v[196:197], off
	global_load_dwordx4 v[154:157], v[198:199], off
	v_lshl_add_u64 v[202:203], v[138:139], 0, v[220:221]
	global_load_dwordx4 v[150:153], v[200:201], off
	global_load_dwordx4 v[146:149], v[202:203], off
	v_lshl_add_u64 v[210:211], v[138:139], 0, v[216:217]
	global_load_dwordx4 v[142:145], v[204:205], off
	global_load_dwordx4 v[138:141], v[210:211], off
	v_addc_co_u32_e32 v189, vcc, 0, v189, vcc
	global_load_dword v128, v[188:189], off
	global_load_dword v163, v[188:189], off offset:64
	global_load_dword v165, v[188:189], off offset:128
	global_load_dword v167, v[188:189], off offset:192
	global_load_dword v169, v[188:189], off offset:512
	global_load_dword v171, v[188:189], off offset:576
	global_load_dword v173, v[188:189], off offset:640
	global_load_dword v250, v[192:193], off offset:256
	global_load_dword v250, v[194:195], off offset:256
	global_load_dword v250, v[196:197], off offset:256
	global_load_dword v250, v[198:199], off offset:256
	global_load_dword v250, v[200:201], off offset:256
	global_load_dword v250, v[202:203], off offset:256
	global_load_dword v250, v[204:205], off offset:256
	global_load_dword v250, v[210:211], off offset:256
	v_lshl_add_u64 v[208:209], s[96:97], 0, v[208:209]
	v_lshl_add_u64 v[208:209], v[208:209], 0, v[206:207]
	s_waitcnt vmcnt(0)
	v_cvt_f32_f16_e32 v250, v212
	v_cvt_f32_f16_sdwa v251, v212 dst_sel:DWORD dst_unused:UNUSED_PAD src0_sel:WORD_1
	v_cvt_f32_f16_e32 v212, v213
	v_cvt_f32_f16_sdwa v213, v213 dst_sel:DWORD dst_unused:UNUSED_PAD src0_sel:WORD_1
	v_cvt_f32_f16_e32 v174, v214
	v_fmamk_f32 v128, v128, 0x3b2aaaab, v227
	s_nop 1
	v_rsq_f32_e32 v128, v128
	v_cvt_f32_f16_sdwa v175, v214 dst_sel:DWORD dst_unused:UNUSED_PAD src0_sel:WORD_1
	v_cvt_f32_f16_e32 v214, v215
	v_cvt_f32_f16_sdwa v215, v215 dst_sel:DWORD dst_unused:UNUSED_PAD src0_sel:WORD_1
	v_pk_mul_f32 v[124:125], v[124:125], v[128:129] op_sel_hi:[1,0]
	v_pk_mul_f32 v[126:127], v[126:127], v[128:129] op_sel_hi:[1,0]
	v_pk_mul_f32 v[176:177], v[120:121], v[128:129] op_sel_hi:[1,0]
	v_pk_mul_f32 v[122:123], v[122:123], v[128:129] op_sel_hi:[1,0]
	v_pk_fma_f32 v[120:121], v[136:137], v[126:127], v[212:213]
	v_pk_fma_f32 v[124:125], v[134:135], v[124:125], v[250:251]
	v_pk_fma_f32 v[122:123], v[132:133], v[122:123], v[214:215]
	v_pk_fma_f32 v[126:127], v[130:131], v[176:177], v[174:175]
	v_cvt_pk_f16_f32 v212, v124, v125
	v_cvt_pk_f16_f32 v213, v120, v121
	v_cvt_pk_f16_f32 v214, v126, v127
	v_cvt_pk_f16_f32 v215, v122, v123
	global_store_dwordx4 v[208:209], v[212:215], off
	s_nop 0
	v_lshl_add_u64 v[174:175], s[96:97], 0, v[246:247]
	v_lshl_add_u64 v[212:213], v[174:175], 0, v[206:207]
	v_cvt_f32_f16_e32 v174, v242
	v_cvt_f32_f16_sdwa v175, v242 dst_sel:DWORD dst_unused:UNUSED_PAD src0_sel:WORD_1
	v_cvt_f32_f16_e32 v176, v243
	v_cvt_f32_f16_sdwa v177, v243 dst_sel:DWORD dst_unused:UNUSED_PAD src0_sel:WORD_1
	v_cvt_f32_f16_e32 v214, v244
	v_cvt_f32_f16_e32 v242, v245
	v_cvt_f32_f16_sdwa v243, v245 dst_sel:DWORD dst_unused:UNUSED_PAD src0_sel:WORD_1
	v_fmamk_f32 v128, v163, 0x3b2aaaab, v227
	s_nop 1
	v_rsq_f32_e32 v128, v128
	v_cvt_f32_f16_sdwa v215, v244 dst_sel:DWORD dst_unused:UNUSED_PAD src0_sel:WORD_1
	v_pk_mul_f32 v[244:245], v[116:117], v[128:129] op_sel_hi:[1,0]
	v_pk_mul_f32 v[116:117], v[118:119], v[128:129] op_sel_hi:[1,0]
	v_pk_mul_f32 v[246:247], v[112:113], v[128:129] op_sel_hi:[1,0]
	v_pk_mul_f32 v[112:113], v[114:115], v[128:129] op_sel_hi:[1,0]
	v_pk_fma_f32 v[116:117], v[136:137], v[116:117], v[176:177]
	v_pk_fma_f32 v[118:119], v[134:135], v[244:245], v[174:175]
	v_pk_fma_f32 v[112:113], v[132:133], v[112:113], v[242:243]
	v_pk_fma_f32 v[114:115], v[130:131], v[246:247], v[214:215]
	v_cvt_pk_f16_f32 v242, v118, v119
	v_cvt_pk_f16_f32 v243, v116, v117
	v_cvt_pk_f16_f32 v244, v114, v115
	v_cvt_pk_f16_f32 v245, v112, v113
	global_store_dwordx4 v[212:213], v[242:245], off
	s_nop 0
	v_lshl_add_u64 v[174:175], s[96:97], 0, v[248:249]
; __device__ __forceinline__ unsigned pk_f16(float lo, float hi) { f32x2 v = {lo, hi}; f16x2_t h = __builtin_convertvector(v, f16x2_t); return __builtin_bit_cast(unsigned, h); }
; __device__ __forceinline__ f32x2 up_f16(unsigned w) { return __builtin_convertvector(__builtin_bit_cast(f16x2_t, w), f32x2); }
;     __device__ __forceinline__ void operator()(const f32x4 (&acc)[2][2][4][2], const Unit& u, int wr, int wc, int fr, int fq) const {
;     ...
;             for (int n = 0; n < 2; ++n) gv[n] = *(const f32x4*)(gate + (size_t)b * gstride + col0 + bj * HALF + 4 * n);
;             u32x4 pq[2][4];
; #pragma unroll
;             for (int ai = 0; ai < 2; ++ai)
; #pragma unroll
;                 for (int m = 0; m < 4; ++m) pq[ai][m] = *(const u32x4*)(base + (size_t)(row0 + ai * HALF + m * 16) * 1024 + col0 + bj * HALF);
;             asm volatile("" ::: "memory");
; #pragma unroll
;             for (int ai = 0; ai < 2; ++ai) {
; #pragma unroll
;                 for (int m = 0; m < 4; ++m) { const size_t off = (size_t)(row0 + ai * HALF + m * 16) * 1024 + col0 + bj * HALF;
;                     float rc = 1.0f; if constexpr (GN) rc = rsqrtf(gss[2 * 32768 + row0 + ai * HALF + m * 16] * (1.0f / 384.0f) + 1e-6f);
;                     const u32x4 q = pq[ai][m];
;                     const f32x2 qa_ = up_f16(q.x), qb_ = up_f16(q.y), qc_ = up_f16(q.z), qd_ = up_f16(q.w);
;                     const f32x4 x0 = (f32x4){qa_[0], qa_[1], qb_[0], qb_[1]} + gv[0] * (acc[ai][bj][m][0] * rc),
;                                 x1 = (f32x4){qc_[0], qc_[1], qd_[0], qd_[1]} + gv[1] * (acc[ai][bj][m][1] * rc);
;                     { u32x4 wx; wx.x = pk_f16(x0[0], x0[1]); wx.y = pk_f16(x0[2], x0[3]); wx.z = pk_f16(x1[0], x1[1]); wx.w = pk_f16(x1[2], x1[3]); *(u32x4*)(out + off) = wx; }
	v_lshl_add_u64 v[214:215], v[174:175], 0, v[206:207]
	v_cvt_f32_f16_e32 v174, v158
	v_cvt_f32_f16_sdwa v175, v158 dst_sel:DWORD dst_unused:UNUSED_PAD src0_sel:WORD_1
	v_cvt_f32_f16_e32 v158, v159
	v_cvt_f32_f16_sdwa v159, v159 dst_sel:DWORD dst_unused:UNUSED_PAD src0_sel:WORD_1
	v_cvt_f32_f16_e32 v176, v160
	v_fmamk_f32 v128, v165, 0x3b2aaaab, v227
	s_nop 1
	v_rsq_f32_e32 v128, v128
	v_cvt_f32_f16_sdwa v177, v160 dst_sel:DWORD dst_unused:UNUSED_PAD src0_sel:WORD_1
	v_cvt_f32_f16_e32 v160, v161
	v_cvt_f32_f16_sdwa v161, v161 dst_sel:DWORD dst_unused:UNUSED_PAD src0_sel:WORD_1
	v_pk_mul_f32 v[242:243], v[108:109], v[128:129] op_sel_hi:[1,0]
	v_pk_mul_f32 v[108:109], v[110:111], v[128:129] op_sel_hi:[1,0]
	v_pk_mul_f32 v[244:245], v[104:105], v[128:129] op_sel_hi:[1,0]
	v_pk_mul_f32 v[104:105], v[106:107], v[128:129] op_sel_hi:[1,0]
	v_pk_fma_f32 v[108:109], v[136:137], v[108:109], v[158:159]
	v_pk_fma_f32 v[110:111], v[134:135], v[242:243], v[174:175]
	v_pk_fma_f32 v[104:105], v[132:133], v[104:105], v[160:161]
	v_pk_fma_f32 v[106:107], v[130:131], v[244:245], v[176:177]
	v_cvt_pk_f16_f32 v158, v110, v111
	v_cvt_pk_f16_f32 v159, v108, v109
	v_cvt_pk_f16_f32 v160, v106, v107
	v_cvt_pk_f16_f32 v161, v104, v105
	global_store_dwordx4 v[214:215], v[158:161], off
	s_nop 0
	v_cvt_f32_f16_e32 v174, v156
	v_cvt_f32_f16_e32 v160, v154
	v_cvt_f32_f16_sdwa v161, v154 dst_sel:DWORD dst_unused:UNUSED_PAD src0_sel:WORD_1
	v_cvt_f32_f16_e32 v154, v155
	v_cvt_f32_f16_sdwa v155, v155 dst_sel:DWORD dst_unused:UNUSED_PAD src0_sel:WORD_1
	v_lshl_add_u64 v[158:159], s[96:97], 0, v[224:225]
	v_lshl_add_u64 v[158:159], v[158:159], 0, v[206:207]
	v_fmamk_f32 v128, v167, 0x3b2aaaab, v227
	s_nop 1
	v_rsq_f32_e32 v128, v128
	v_cvt_f32_f16_sdwa v175, v156 dst_sel:DWORD dst_unused:UNUSED_PAD src0_sel:WORD_1
	v_cvt_f32_f16_e32 v156, v157
	v_cvt_f32_f16_sdwa v157, v157 dst_sel:DWORD dst_unused:UNUSED_PAD src0_sel:WORD_1
	v_pk_mul_f32 v[176:177], v[100:101], v[128:129] op_sel_hi:[1,0]
	v_pk_mul_f32 v[100:101], v[102:103], v[128:129] op_sel_hi:[1,0]
	v_pk_mul_f32 v[224:225], v[96:97], v[128:129] op_sel_hi:[1,0]
	v_pk_mul_f32 v[96:97], v[98:99], v[128:129] op_sel_hi:[1,0]
	v_pk_fma_f32 v[100:101], v[136:137], v[100:101], v[154:155]
	v_pk_fma_f32 v[102:103], v[134:135], v[176:177], v[160:161]
	v_pk_fma_f32 v[96:97], v[132:133], v[96:97], v[156:157]
	v_pk_fma_f32 v[98:99], v[130:131], v[224:225], v[174:175]
	v_cvt_pk_f16_f32 v154, v102, v103
	v_cvt_pk_f16_f32 v155, v100, v101
	v_cvt_pk_f16_f32 v156, v98, v99
	v_cvt_pk_f16_f32 v157, v96, v97
	global_store_dwordx4 v[158:159], v[154:157], off
	s_nop 0
	v_fmamk_f32 v128, v169, 0x3b2aaaab, v227
	v_lshl_add_u64 v[154:155], s[96:97], 0, v[218:219]
	v_lshl_add_u64 v[218:219], v[154:155], 0, v[206:207]
	v_rsq_f32_e32 v128, v128
	v_cvt_f32_f16_e32 v154, v150
	v_cvt_f32_f16_sdwa v155, v150 dst_sel:DWORD dst_unused:UNUSED_PAD src0_sel:WORD_1
	v_cvt_f32_f16_e32 v150, v151
	v_cvt_f32_f16_sdwa v151, v151 dst_sel:DWORD dst_unused:UNUSED_PAD src0_sel:WORD_1
	v_cvt_f32_f16_e32 v156, v152
	v_cvt_f32_f16_sdwa v157, v152 dst_sel:DWORD dst_unused:UNUSED_PAD src0_sel:WORD_1
	v_cvt_f32_f16_e32 v152, v153
	v_cvt_f32_f16_sdwa v153, v153 dst_sel:DWORD dst_unused:UNUSED_PAD src0_sel:WORD_1
	v_pk_mul_f32 v[160:161], v[92:93], v[128:129] op_sel_hi:[1,0]
	v_pk_mul_f32 v[92:93], v[94:95], v[128:129] op_sel_hi:[1,0]
	v_pk_mul_f32 v[174:175], v[88:89], v[128:129] op_sel_hi:[1,0]
	v_pk_mul_f32 v[88:89], v[90:91], v[128:129] op_sel_hi:[1,0]
	v_pk_fma_f32 v[92:93], v[136:137], v[92:93], v[150:151]
	v_pk_fma_f32 v[94:95], v[134:135], v[160:161], v[154:155]
	v_pk_fma_f32 v[88:89], v[132:133], v[88:89], v[152:153]
	v_pk_fma_f32 v[90:91], v[130:131], v[174:175], v[156:157]
	v_cvt_pk_f16_f32 v150, v94, v95
	v_cvt_pk_f16_f32 v151, v92, v93
	v_cvt_pk_f16_f32 v152, v90, v91
	v_cvt_pk_f16_f32 v153, v88, v89
	global_store_dwordx4 v[218:219], v[150:153], off
	s_nop 0
	v_cvt_f32_f16_e32 v154, v148
	v_lshl_add_u64 v[150:151], s[96:97], 0, v[220:221]
	v_lshl_add_u64 v[220:221], v[150:151], 0, v[206:207]
	v_cvt_f32_f16_e32 v152, v146
	v_cvt_f32_f16_sdwa v153, v146 dst_sel:DWORD dst_unused:UNUSED_PAD src0_sel:WORD_1
	v_cvt_f32_f16_e32 v146, v147
	v_cvt_f32_f16_sdwa v147, v147 dst_sel:DWORD dst_unused:UNUSED_PAD src0_sel:WORD_1
	v_cvt_f32_f16_sdwa v155, v148 dst_sel:DWORD dst_unused:UNUSED_PAD src0_sel:WORD_1
	v_cvt_f32_f16_e32 v148, v149
	v_cvt_f32_f16_sdwa v149, v149 dst_sel:DWORD dst_unused:UNUSED_PAD src0_sel:WORD_1
	v_fmamk_f32 v128, v171, 0x3b2aaaab, v227
	s_nop 1
	v_rsq_f32_e32 v128, v128
	s_nop 0
	v_pk_mul_f32 v[84:85], v[84:85], v[128:129] op_sel_hi:[1,0]
	v_pk_mul_f32 v[86:87], v[86:87], v[128:129] op_sel_hi:[1,0]
	v_pk_mul_f32 v[80:81], v[80:81], v[128:129] op_sel_hi:[1,0]
	v_pk_mul_f32 v[82:83], v[82:83], v[128:129] op_sel_hi:[1,0]
	v_pk_fma_f32 v[150:151], v[136:137], v[86:87], v[146:147]
	v_pk_fma_f32 v[152:153], v[134:135], v[84:85], v[152:153]
	v_pk_fma_f32 v[146:147], v[132:133], v[82:83], v[148:149]
	v_pk_fma_f32 v[148:149], v[130:131], v[80:81], v[154:155]
	v_cvt_pk_f16_f32 v80, v152, v153
	v_cvt_pk_f16_f32 v81, v150, v151
	v_cvt_pk_f16_f32 v82, v148, v149
	v_cvt_pk_f16_f32 v83, v146, v147
	global_store_dwordx4 v[220:221], v[80:83], off
	s_nop 0
	v_cvt_f32_f16_e32 v84, v144
	v_lshl_add_u64 v[80:81], s[96:97], 0, v[222:223]
	v_lshl_add_u64 v[222:223], v[80:81], 0, v[206:207]
	v_cvt_f32_f16_e32 v80, v142
	v_cvt_f32_f16_sdwa v81, v142 dst_sel:DWORD dst_unused:UNUSED_PAD src0_sel:WORD_1
	v_cvt_f32_f16_e32 v82, v143
	v_cvt_f32_f16_sdwa v83, v143 dst_sel:DWORD dst_unused:UNUSED_PAD src0_sel:WORD_1
	v_cvt_f32_f16_sdwa v87, v145 dst_sel:DWORD dst_unused:UNUSED_PAD src0_sel:WORD_1
	v_fmamk_f32 v85, v173, 0x3b2aaaab, v227
	s_nop 1
	v_rsq_f32_e32 v128, v85
	v_cvt_f32_f16_sdwa v85, v144 dst_sel:DWORD dst_unused:UNUSED_PAD src0_sel:WORD_1
	v_cvt_f32_f16_e32 v86, v145
	v_pk_mul_f32 v[76:77], v[76:77], v[128:129] op_sel_hi:[1,0]
	v_pk_mul_f32 v[78:79], v[78:79], v[128:129] op_sel_hi:[1,0]
	v_pk_mul_f32 v[72:73], v[72:73], v[128:129] op_sel_hi:[1,0]
	v_pk_mul_f32 v[74:75], v[74:75], v[128:129] op_sel_hi:[1,0]
	v_pk_fma_f32 v[154:155], v[136:137], v[78:79], v[82:83]
	v_pk_fma_f32 v[156:157], v[134:135], v[76:77], v[80:81]
	v_pk_fma_f32 v[142:143], v[132:133], v[74:75], v[86:87]
	v_pk_fma_f32 v[144:145], v[130:131], v[72:73], v[84:85]
	v_cvt_pk_f16_f32 v72, v156, v157
	v_cvt_pk_f16_f32 v73, v154, v155
	v_cvt_pk_f16_f32 v74, v144, v145
	v_cvt_pk_f16_f32 v75, v142, v143
	global_store_dwordx4 v[222:223], v[72:75], off
	global_load_dword v77, v[188:189], off offset:704
	v_cvt_f32_f16_e32 v76, v140
	v_lshl_add_u64 v[72:73], s[96:97], 0, v[216:217]
	v_lshl_add_u64 v[160:161], v[72:73], 0, v[206:207]
	v_cvt_f32_f16_e32 v72, v138
	v_cvt_f32_f16_sdwa v73, v138 dst_sel:DWORD dst_unused:UNUSED_PAD src0_sel:WORD_1
	v_cvt_f32_f16_e32 v74, v139
	v_cvt_f32_f16_sdwa v75, v139 dst_sel:DWORD dst_unused:UNUSED_PAD src0_sel:WORD_1
	v_cvt_f32_f16_sdwa v79, v141 dst_sel:DWORD dst_unused:UNUSED_PAD src0_sel:WORD_1
	s_waitcnt vmcnt(0)
; __device__ __forceinline__ unsigned pk_f16(float lo, float hi) { f32x2 v = {lo, hi}; f16x2_t h = __builtin_convertvector(v, f16x2_t); return __builtin_bit_cast(unsigned, h); }
; __device__ __forceinline__ f32x2 up_f16(unsigned w) { return __builtin_convertvector(__builtin_bit_cast(f16x2_t, w), f32x2); }
;     __device__ __forceinline__ void operator()(const f32x4 (&acc)[2][2][4][2], const Unit& u, int wr, int wc, int fr, int fq) const {
;     ...
;         for (int bj = 0; bj < 2; ++bj) {
;             f32x4 gv[2];
; #pragma unroll
;             for (int n = 0; n < 2; ++n) gv[n] = *(const f32x4*)(gate + (size_t)b * gstride + col0 + bj * HALF + 4 * n);
;             u32x4 pq[2][4];
; #pragma unroll
;             for (int ai = 0; ai < 2; ++ai)
; #pragma unroll
;                 for (int m = 0; m < 4; ++m) pq[ai][m] = *(const u32x4*)(base + (size_t)(row0 + ai * HALF + m * 16) * 1024 + col0 + bj * HALF);
;             asm volatile("" ::: "memory");
; #pragma unroll
;             for (int ai = 0; ai < 2; ++ai) {
; #pragma unroll
;                 for (int m = 0; m < 4; ++m) { const size_t off = (size_t)(row0 + ai * HALF + m * 16) * 1024 + col0 + bj * HALF;
;                     float rc = 1.0f; if constexpr (GN) rc = rsqrtf(gss[2 * 32768 + row0 + ai * HALF + m * 16] * (1.0f / 384.0f) + 1e-6f);
;                     const u32x4 q = pq[ai][m];
;                     const f32x2 qa_ = up_f16(q.x), qb_ = up_f16(q.y), qc_ = up_f16(q.z), qd_ = up_f16(q.w);
;                     const f32x4 x0 = (f32x4){qa_[0], qa_[1], qb_[0], qb_[1]} + gv[0] * (acc[ai][bj][m][0] * rc),
;                                 x1 = (f32x4){qc_[0], qc_[1], qd_[0], qd_[1]} + gv[1] * (acc[ai][bj][m][1] * rc);
;                     { u32x4 wx; wx.x = pk_f16(x0[0], x0[1]); wx.y = pk_f16(x0[2], x0[3]); wx.z = pk_f16(x1[0], x1[1]); wx.w = pk_f16(x1[2], x1[3]); *(u32x4*)(out + off) = wx; }
;                     ss[ai][m] += ((x0[0] * x0[0] + x0[1] * x0[1]) + (x0[2] * x0[2] + x0[3] * x0[3])) + ((x1[0] * x1[0] + x1[1] * x1[1]) + (x1[2] * x1[2] + x1[3] * x1[3]));
	v_fmamk_f32 v77, v77, 0x3b2aaaab, v227
	s_nop 1
	v_rsq_f32_e32 v80, v77
	v_cvt_f32_f16_sdwa v77, v140 dst_sel:DWORD dst_unused:UNUSED_PAD src0_sel:WORD_1
	v_cvt_f32_f16_e32 v78, v141
	v_pk_mul_f32 v[68:69], v[68:69], v[80:81] op_sel_hi:[1,0]
	v_pk_mul_f32 v[70:71], v[70:71], v[80:81] op_sel_hi:[1,0]
	v_pk_mul_f32 v[64:65], v[64:65], v[80:81] op_sel_hi:[1,0]
	v_pk_mul_f32 v[66:67], v[66:67], v[80:81] op_sel_hi:[1,0]
	v_pk_fma_f32 v[136:137], v[136:137], v[70:71], v[74:75]
	v_pk_fma_f32 v[134:135], v[134:135], v[68:69], v[72:73]
	v_pk_fma_f32 v[132:133], v[132:133], v[66:67], v[78:79]
	v_pk_fma_f32 v[130:131], v[130:131], v[64:65], v[76:77]
	v_cvt_pk_f16_f32 v64, v134, v135
	v_cvt_pk_f16_f32 v65, v136, v137
	v_cvt_pk_f16_f32 v66, v130, v131
	v_cvt_pk_f16_f32 v67, v132, v133
	global_store_dwordx4 v[160:161], v[64:67], off
	global_load_dwordx4 v[64:67], v[190:191], off offset:528
	global_load_dwordx4 v[68:71], v[190:191], off offset:512
	global_load_dwordx4 v[138:141], v[192:193], off offset:256
	s_nop 0
	global_load_dwordx4 v[190:193], v[194:195], off offset:256
	s_nop 0
	global_load_dwordx4 v[194:197], v[196:197], off offset:256
	s_nop 0
	global_load_dwordx4 v[242:245], v[198:199], off offset:256
	global_load_dwordx4 v[84:87], v[200:201], off offset:256
	global_load_dwordx4 v[80:83], v[202:203], off offset:256
	global_load_dwordx4 v[76:79], v[204:205], off offset:256
	global_load_dwordx4 v[72:75], v[210:211], off offset:256
	global_load_dword v128, v[188:189], off
	s_waitcnt vmcnt(8)
	v_cvt_f32_f16_e32 v174, v138
	v_cvt_f32_f16_sdwa v175, v138 dst_sel:DWORD dst_unused:UNUSED_PAD src0_sel:WORD_1
	v_cvt_f32_f16_e32 v138, v139
	v_cvt_f32_f16_sdwa v139, v139 dst_sel:DWORD dst_unused:UNUSED_PAD src0_sel:WORD_1
	v_cvt_f32_f16_e32 v176, v140
	s_waitcnt vmcnt(0)
	v_fmamk_f32 v128, v128, 0x3b2aaaab, v227
	s_nop 1
	v_rsq_f32_e32 v128, v128
	v_cvt_f32_f16_sdwa v177, v140 dst_sel:DWORD dst_unused:UNUSED_PAD src0_sel:WORD_1
	v_cvt_f32_f16_e32 v140, v141
	v_cvt_f32_f16_sdwa v141, v141 dst_sel:DWORD dst_unused:UNUSED_PAD src0_sel:WORD_1
	v_pk_mul_f32 v[60:61], v[60:61], v[128:129] op_sel_hi:[1,0]
	v_pk_mul_f32 v[62:63], v[62:63], v[128:129] op_sel_hi:[1,0]
	v_pk_mul_f32 v[198:199], v[56:57], v[128:129] op_sel_hi:[1,0]
	v_pk_mul_f32 v[200:201], v[58:59], v[128:129] op_sel_hi:[1,0]
	v_pk_fma_f32 v[56:57], v[70:71], v[62:63], v[138:139]
	v_pk_fma_f32 v[58:59], v[68:69], v[60:61], v[174:175]
	v_pk_fma_f32 v[60:61], v[66:67], v[200:201], v[140:141]
	v_pk_fma_f32 v[62:63], v[64:65], v[198:199], v[176:177]
	v_cvt_pk_f16_f32 v138, v58, v59
	v_cvt_pk_f16_f32 v139, v56, v57
	v_cvt_pk_f16_f32 v140, v62, v63
	v_cvt_pk_f16_f32 v141, v60, v61
	global_store_dwordx4 v[208:209], v[138:141], off offset:256
	s_nop 0
	v_cvt_f32_f16_e32 v174, v192
	v_cvt_f32_f16_e32 v138, v190
	v_cvt_f32_f16_sdwa v139, v190 dst_sel:DWORD dst_unused:UNUSED_PAD src0_sel:WORD_1
	v_cvt_f32_f16_e32 v140, v191
	v_cvt_f32_f16_sdwa v141, v191 dst_sel:DWORD dst_unused:UNUSED_PAD src0_sel:WORD_1
	v_cvt_f32_f16_e32 v176, v193
	v_cvt_f32_f16_sdwa v177, v193 dst_sel:DWORD dst_unused:UNUSED_PAD src0_sel:WORD_1
	v_mul_f32_e32 v59, v59, v59
	v_mul_f32_e32 v57, v57, v57
	v_mul_f32_e32 v63, v63, v63
	v_mul_f32_e32 v61, v61, v61
	v_fmac_f32_e32 v59, v58, v58
	v_fmac_f32_e32 v57, v56, v56
	v_fmac_f32_e32 v63, v62, v62
	v_fmac_f32_e32 v61, v60, v60
	v_add_f32_e32 v56, v59, v57
	v_add_f32_e32 v57, v63, v61
	v_add_f32_e32 v56, v56, v57
	v_cvt_f32_f16_e32 v60, v75
	v_cvt_f32_f16_sdwa v61, v75 dst_sel:DWORD dst_unused:UNUSED_PAD src0_sel:WORD_1
	v_fmamk_f32 v128, v163, 0x3b2aaaab, v227
	s_nop 1
	v_rsq_f32_e32 v128, v128
	v_cvt_f32_f16_sdwa v175, v192 dst_sel:DWORD dst_unused:UNUSED_PAD src0_sel:WORD_1
	v_pk_mul_f32 v[190:191], v[52:53], v[128:129] op_sel_hi:[1,0]
	v_pk_mul_f32 v[52:53], v[54:55], v[128:129] op_sel_hi:[1,0]
	v_pk_mul_f32 v[192:193], v[48:49], v[128:129] op_sel_hi:[1,0]
	v_pk_mul_f32 v[48:49], v[50:51], v[128:129] op_sel_hi:[1,0]
	v_pk_fma_f32 v[52:53], v[70:71], v[52:53], v[140:141]
	v_pk_fma_f32 v[54:55], v[68:69], v[190:191], v[138:139]
	v_pk_fma_f32 v[48:49], v[66:67], v[48:49], v[176:177]
	v_pk_fma_f32 v[50:51], v[64:65], v[192:193], v[174:175]
	v_cvt_pk_f16_f32 v138, v54, v55
	v_cvt_pk_f16_f32 v139, v52, v53
	v_cvt_pk_f16_f32 v140, v50, v51
	v_cvt_pk_f16_f32 v141, v48, v49
	global_store_dwordx4 v[212:213], v[138:141], off offset:256
	s_nop 0
	v_cvt_f32_f16_e32 v174, v196
	v_cvt_f32_f16_e32 v138, v194
	v_cvt_f32_f16_sdwa v139, v194 dst_sel:DWORD dst_unused:UNUSED_PAD src0_sel:WORD_1
	v_cvt_f32_f16_e32 v140, v195
	v_cvt_f32_f16_sdwa v141, v195 dst_sel:DWORD dst_unused:UNUSED_PAD src0_sel:WORD_1
	v_cvt_f32_f16_e32 v176, v197
	v_cvt_f32_f16_sdwa v177, v197 dst_sel:DWORD dst_unused:UNUSED_PAD src0_sel:WORD_1
	v_fmamk_f32 v128, v165, 0x3b2aaaab, v227
	s_nop 1
	v_rsq_f32_e32 v128, v128
	v_cvt_f32_f16_sdwa v175, v196 dst_sel:DWORD dst_unused:UNUSED_PAD src0_sel:WORD_1
	v_pk_mul_f32 v[190:191], v[44:45], v[128:129] op_sel_hi:[1,0]
	v_pk_mul_f32 v[44:45], v[46:47], v[128:129] op_sel_hi:[1,0]
	v_pk_mul_f32 v[192:193], v[40:41], v[128:129] op_sel_hi:[1,0]
	v_pk_mul_f32 v[40:41], v[42:43], v[128:129] op_sel_hi:[1,0]
	v_pk_fma_f32 v[44:45], v[70:71], v[44:45], v[140:141]
	v_pk_fma_f32 v[46:47], v[68:69], v[190:191], v[138:139]
	v_pk_fma_f32 v[40:41], v[66:67], v[40:41], v[176:177]
	v_pk_fma_f32 v[42:43], v[64:65], v[192:193], v[174:175]
	v_cvt_pk_f16_f32 v138, v46, v47
	v_cvt_pk_f16_f32 v139, v44, v45
	v_cvt_pk_f16_f32 v140, v42, v43
	v_cvt_pk_f16_f32 v141, v40, v41
	global_store_dwordx4 v[214:215], v[138:141], off offset:256
	s_nop 0
	v_cvt_f32_f16_e32 v174, v244
	v_cvt_f32_f16_e32 v138, v242
; __device__ __forceinline__ unsigned pk_f16(float lo, float hi) { f32x2 v = {lo, hi}; f16x2_t h = __builtin_convertvector(v, f16x2_t); return __builtin_bit_cast(unsigned, h); }
; __device__ __forceinline__ f32x2 up_f16(unsigned w) { return __builtin_convertvector(__builtin_bit_cast(f16x2_t, w), f32x2); }
;     __device__ __forceinline__ void operator()(const f32x4 (&acc)[2][2][4][2], const Unit& u, int wr, int wc, int fr, int fq) const {
;     ...
;             for (int ai = 0; ai < 2; ++ai) {
; #pragma unroll
;                 for (int m = 0; m < 4; ++m) { const size_t off = (size_t)(row0 + ai * HALF + m * 16) * 1024 + col0 + bj * HALF;
;                     float rc = 1.0f; if constexpr (GN) rc = rsqrtf(gss[2 * 32768 + row0 + ai * HALF + m * 16] * (1.0f / 384.0f) + 1e-6f);
;                     const u32x4 q = pq[ai][m];
;                     const f32x2 qa_ = up_f16(q.x), qb_ = up_f16(q.y), qc_ = up_f16(q.z), qd_ = up_f16(q.w);
;                     const f32x4 x0 = (f32x4){qa_[0], qa_[1], qb_[0], qb_[1]} + gv[0] * (acc[ai][bj][m][0] * rc),
;                                 x1 = (f32x4){qc_[0], qc_[1], qd_[0], qd_[1]} + gv[1] * (acc[ai][bj][m][1] * rc);
;                     { u32x4 wx; wx.x = pk_f16(x0[0], x0[1]); wx.y = pk_f16(x0[2], x0[3]); wx.z = pk_f16(x1[0], x1[1]); wx.w = pk_f16(x1[2], x1[3]); *(u32x4*)(out + off) = wx; }
;                     ss[ai][m] += ((x0[0] * x0[0] + x0[1] * x0[1]) + (x0[2] * x0[2] + x0[3] * x0[3])) + ((x1[0] * x1[0] + x1[1] * x1[1]) + (x1[2] * x1[2] + x1[3] * x1[3]));
;                 }
;                 asm volatile("" ::: "memory");
;             }
;         }
; #pragma unroll
;         for (int ai = 0; ai < 2; ++ai)
; #pragma unroll
;             for (int m = 0; m < 4; ++m) { float t = ss[ai][m]; t += __shfl_xor(t, 16); t += __shfl_xor(t, 32);
;                 if (fq == 0) atomicAdd(rowss + row0 + ai * HALF + m * 16, t); }
;     }
	v_cvt_f32_f16_sdwa v139, v242 dst_sel:DWORD dst_unused:UNUSED_PAD src0_sel:WORD_1
	v_cvt_f32_f16_e32 v140, v243
	v_cvt_f32_f16_sdwa v141, v243 dst_sel:DWORD dst_unused:UNUSED_PAD src0_sel:WORD_1
	v_cvt_f32_f16_e32 v176, v245
	v_cvt_f32_f16_sdwa v177, v245 dst_sel:DWORD dst_unused:UNUSED_PAD src0_sel:WORD_1
	v_fmamk_f32 v128, v167, 0x3b2aaaab, v227
	s_nop 1
	v_rsq_f32_e32 v128, v128
	v_cvt_f32_f16_sdwa v175, v244 dst_sel:DWORD dst_unused:UNUSED_PAD src0_sel:WORD_1
	v_pk_mul_f32 v[190:191], v[36:37], v[128:129] op_sel_hi:[1,0]
	v_pk_mul_f32 v[36:37], v[38:39], v[128:129] op_sel_hi:[1,0]
	v_pk_mul_f32 v[192:193], v[32:33], v[128:129] op_sel_hi:[1,0]
	v_pk_mul_f32 v[32:33], v[34:35], v[128:129] op_sel_hi:[1,0]
	v_pk_fma_f32 v[36:37], v[70:71], v[36:37], v[140:141]
	v_pk_fma_f32 v[38:39], v[68:69], v[190:191], v[138:139]
	v_pk_fma_f32 v[32:33], v[66:67], v[32:33], v[176:177]
	v_pk_fma_f32 v[34:35], v[64:65], v[192:193], v[174:175]
	v_cvt_pk_f16_f32 v138, v38, v39
	v_cvt_pk_f16_f32 v139, v36, v37
	v_cvt_pk_f16_f32 v140, v34, v35
	v_cvt_pk_f16_f32 v141, v32, v33
	global_store_dwordx4 v[158:159], v[138:141], off offset:256
	s_nop 0
	v_fmamk_f32 v128, v169, 0x3b2aaaab, v227
	v_cvt_f32_f16_e32 v138, v84
	v_cvt_f32_f16_sdwa v139, v84 dst_sel:DWORD dst_unused:UNUSED_PAD src0_sel:WORD_1
	v_rsq_f32_e32 v128, v128
	v_cvt_f32_f16_e32 v84, v85
	v_cvt_f32_f16_sdwa v85, v85 dst_sel:DWORD dst_unused:UNUSED_PAD src0_sel:WORD_1
	v_cvt_f32_f16_e32 v140, v86
	v_cvt_f32_f16_sdwa v141, v86 dst_sel:DWORD dst_unused:UNUSED_PAD src0_sel:WORD_1
	v_cvt_f32_f16_e32 v86, v87
	v_cvt_f32_f16_sdwa v87, v87 dst_sel:DWORD dst_unused:UNUSED_PAD src0_sel:WORD_1
	v_pk_mul_f32 v[158:159], v[28:29], v[128:129] op_sel_hi:[1,0]
	v_pk_mul_f32 v[28:29], v[30:31], v[128:129] op_sel_hi:[1,0]
	v_pk_mul_f32 v[174:175], v[24:25], v[128:129] op_sel_hi:[1,0]
	v_pk_mul_f32 v[24:25], v[26:27], v[128:129] op_sel_hi:[1,0]
	v_pk_fma_f32 v[28:29], v[70:71], v[28:29], v[84:85]
	v_pk_fma_f32 v[30:31], v[68:69], v[158:159], v[138:139]
	v_pk_fma_f32 v[24:25], v[66:67], v[24:25], v[86:87]
	v_pk_fma_f32 v[26:27], v[64:65], v[174:175], v[140:141]
	v_cvt_pk_f16_f32 v84, v30, v31
	v_cvt_pk_f16_f32 v85, v28, v29
	v_cvt_pk_f16_f32 v86, v26, v27
	v_cvt_pk_f16_f32 v87, v24, v25
	global_store_dwordx4 v[218:219], v[84:87], off offset:256
	s_nop 0
	s_nop 0
	v_cvt_f32_f16_e32 v84, v80
	v_cvt_f32_f16_sdwa v85, v80 dst_sel:DWORD dst_unused:UNUSED_PAD src0_sel:WORD_1
	v_cvt_f32_f16_e32 v80, v81
	v_cvt_f32_f16_sdwa v81, v81 dst_sel:DWORD dst_unused:UNUSED_PAD src0_sel:WORD_1
	v_cvt_f32_f16_e32 v86, v82
	v_fmamk_f32 v87, v171, 0x3b2aaaab, v227
	s_nop 1
	v_rsq_f32_e32 v128, v87
	v_cvt_f32_f16_sdwa v87, v82 dst_sel:DWORD dst_unused:UNUSED_PAD src0_sel:WORD_1
	v_cvt_f32_f16_e32 v82, v83
	v_cvt_f32_f16_sdwa v83, v83 dst_sel:DWORD dst_unused:UNUSED_PAD src0_sel:WORD_1
	v_pk_mul_f32 v[138:139], v[20:21], v[128:129] op_sel_hi:[1,0]
	v_pk_mul_f32 v[20:21], v[22:23], v[128:129] op_sel_hi:[1,0]
	v_pk_mul_f32 v[140:141], v[16:17], v[128:129] op_sel_hi:[1,0]
	v_pk_mul_f32 v[16:17], v[18:19], v[128:129] op_sel_hi:[1,0]
	v_pk_fma_f32 v[20:21], v[70:71], v[20:21], v[80:81]
	v_pk_fma_f32 v[22:23], v[68:69], v[138:139], v[84:85]
	v_pk_fma_f32 v[16:17], v[66:67], v[16:17], v[82:83]
	v_pk_fma_f32 v[18:19], v[64:65], v[140:141], v[86:87]
	v_cvt_pk_f16_f32 v80, v22, v23
	v_cvt_pk_f16_f32 v81, v20, v21
	v_cvt_pk_f16_f32 v82, v18, v19
	v_cvt_pk_f16_f32 v83, v16, v17
	global_store_dwordx4 v[220:221], v[80:83], off offset:256
	s_nop 0
	s_nop 0
	v_cvt_f32_f16_e32 v80, v76
	v_cvt_f32_f16_sdwa v81, v76 dst_sel:DWORD dst_unused:UNUSED_PAD src0_sel:WORD_1
	v_cvt_f32_f16_e32 v76, v77
	v_cvt_f32_f16_sdwa v77, v77 dst_sel:DWORD dst_unused:UNUSED_PAD src0_sel:WORD_1
	v_cvt_f32_f16_e32 v82, v78
	v_fmamk_f32 v83, v173, 0x3b2aaaab, v227
	v_mov_b32_e32 v163, v129
	v_mov_b32_e32 v165, v129
	v_mov_b32_e32 v167, v129
	v_mov_b32_e32 v169, v129
	v_mov_b32_e32 v171, v129
	v_mov_b32_e32 v173, v129
	s_nop 1
	v_rsq_f32_e32 v84, v83
	v_cvt_f32_f16_sdwa v83, v78 dst_sel:DWORD dst_unused:UNUSED_PAD src0_sel:WORD_1
	v_cvt_f32_f16_e32 v78, v79
	v_cvt_f32_f16_sdwa v79, v79 dst_sel:DWORD dst_unused:UNUSED_PAD src0_sel:WORD_1
	v_pk_mul_f32 v[86:87], v[12:13], v[84:85] op_sel_hi:[1,0]
	v_pk_mul_f32 v[12:13], v[14:15], v[84:85] op_sel_hi:[1,0]
	v_pk_mul_f32 v[138:139], v[8:9], v[84:85] op_sel_hi:[1,0]
	v_pk_mul_f32 v[8:9], v[10:11], v[84:85] op_sel_hi:[1,0]
	v_pk_fma_f32 v[12:13], v[70:71], v[12:13], v[76:77]
	v_pk_fma_f32 v[14:15], v[68:69], v[86:87], v[80:81]
	v_pk_fma_f32 v[8:9], v[66:67], v[8:9], v[78:79]
	v_pk_fma_f32 v[10:11], v[64:65], v[138:139], v[82:83]
	v_cvt_pk_f16_f32 v76, v14, v15
	v_cvt_pk_f16_f32 v77, v12, v13
	v_cvt_pk_f16_f32 v78, v10, v11
	v_cvt_pk_f16_f32 v79, v8, v9
	global_store_dwordx4 v[222:223], v[76:79], off offset:256
	global_load_dword v82, v[188:189], off offset:704
	v_mul_f32_e32 v80, v127, v127
	v_and_b32_e32 v77, 64, v230
	v_xor_b32_e32 v76, 16, v230
	v_add_u32_e32 v77, 64, v77
	v_xor_b32_e32 v78, 32, v230
	v_cmp_lt_i32_e32 vcc, v76, v77
	v_mul_f32_e32 v79, v121, v121
	v_mul_f32_e32 v81, v123, v123
	v_cndmask_b32_e32 v76, v230, v76, vcc
	v_cmp_lt_i32_e32 vcc, v78, v77
	v_lshlrev_b32_e32 v77, 2, v76
	v_fmac_f32_e32 v79, v120, v120
	v_cndmask_b32_e32 v78, v230, v78, vcc
	v_lshlrev_b32_e32 v76, 2, v78
	v_mul_f32_e32 v78, v125, v125
	v_fmac_f32_e32 v78, v124, v124
	v_fmac_f32_e32 v80, v126, v126
	v_fmac_f32_e32 v81, v122, v122
	v_add_f32_e32 v78, v78, v79
	v_add_f32_e32 v79, v80, v81
	v_add_f32_e32 v83, v78, v79
	v_add_f32_e32 v56, v83, v56
	ds_bpermute_b32 v57, v77, v56
	v_cvt_f32_f16_e32 v78, v72
	v_cvt_f32_f16_sdwa v79, v72 dst_sel:DWORD dst_unused:UNUSED_PAD src0_sel:WORD_1
	v_cvt_f32_f16_e32 v72, v73
	v_cvt_f32_f16_sdwa v73, v73 dst_sel:DWORD dst_unused:UNUSED_PAD src0_sel:WORD_1
	v_cvt_f32_f16_e32 v80, v74
	v_cvt_f32_f16_sdwa v81, v74 dst_sel:DWORD dst_unused:UNUSED_PAD src0_sel:WORD_1
	s_waitcnt vmcnt(0)
	v_fmamk_f32 v58, v82, 0x3b2aaaab, v227
	s_nop 1
	v_rsq_f32_e32 v59, v58
	s_waitcnt lgkmcnt(0)
	v_add_f32_e32 v58, v56, v57
	v_mov_b32_e32 v56, v59
	v_pk_mul_f32 v[4:5], v[4:5], v[56:57] op_sel_hi:[1,0]
	v_pk_mul_f32 v[6:7], v[6:7], v[56:57] op_sel_hi:[1,0]
	v_pk_mul_f32 v[0:1], v[0:1], v[56:57] op_sel_hi:[1,0]
	v_pk_mul_f32 v[2:3], v[2:3], v[56:57] op_sel_hi:[1,0]
	v_pk_fma_f32 v[6:7], v[70:71], v[6:7], v[72:73]
	v_pk_fma_f32 v[56:57], v[68:69], v[4:5], v[78:79]
	v_pk_fma_f32 v[2:3], v[66:67], v[2:3], v[60:61]
	v_pk_fma_f32 v[4:5], v[64:65], v[0:1], v[80:81]
	v_cvt_pk_f16_f32 v60, v56, v57
	v_cvt_pk_f16_f32 v61, v6, v7
	v_cvt_pk_f16_f32 v62, v4, v5
	v_cvt_pk_f16_f32 v63, v2, v3
	ds_bpermute_b32 v59, v76, v58
	global_store_dwordx4 v[160:161], v[60:63], off offset:256
	v_lshl_add_u64 v[0:1], v[186:187], 2, s[46:47]
	s_and_saveexec_b64 s[0:1], s[40:41]
	s_cbranch_execz .LBB0_808
	s_waitcnt lgkmcnt(0)
	v_add_f32_e32 v58, v58, v59
	global_atomic_add_f32 v[0:1], v58, off

; __device__ __forceinline__ unsigned pk_f16(float lo, float hi) { f32x2 v = {lo, hi}; f16x2_t h = __builtin_convertvector(v, f16x2_t); return __builtin_bit_cast(unsigned, h); }
;     __device__ __forceinline__ void operator()(const f32x4 (&acc)[2][2][4][2], const Unit& u, int wr, int wc, int fr, int fq) const {
;         const int row0 = u.pm * BM + wr * 64 + fr; const int b = (u.pm * BM) >> 14;
;         int fqo = fq; asm volatile("" : "+v"(fqo));
;         const int col0 = u.pn * BM + wc * 32 + 8 * fqo;
;         float ss[2][4];
; #pragma unroll
;         for (int ai = 0; ai < 2; ++ai)
; #pragma unroll
;             for (int m = 0; m < 4; ++m) ss[ai][m] = 0.f;
; #pragma unroll
;         for (int bj = 0; bj < 2; ++bj) {
;             f32x4 gv[2];
; #pragma unroll
;             for (int n = 0; n < 2; ++n) gv[n] = *(const f32x4*)(gate + (size_t)b * gstride + col0 + bj * HALF + 4 * n);
;             u32x4 pq[2][4];
; #pragma unroll
;             for (int ai = 0; ai < 2; ++ai)
; #pragma unroll
;                 for (int m = 0; m < 4; ++m) pq[ai][m] = *(const u32x4*)(base + (size_t)(row0 + ai * HALF + m * 16) * 1024 + col0 + bj * HALF);
;             asm volatile("" ::: "memory");
; #pragma unroll
;             for (int ai = 0; ai < 2; ++ai) {
; #pragma unroll
;                 for (int m = 0; m < 4; ++m) { const size_t off = (size_t)(row0 + ai * HALF + m * 16) * 1024 + col0 + bj * HALF;
;                     float rc = 1.0f; if constexpr (GN) rc = rsqrtf(gss[2 * 32768 + row0 + ai * HALF + m * 16] * (1.0f / 384.0f) + 1e-6f);
;                     const u32x4 q = pq[ai][m];
;                     const f32x2 qa_ = up_f16(q.x), qb_ = up_f16(q.y), qc_ = up_f16(q.z), qd_ = up_f16(q.w);
;                     const f32x4 x0 = (f32x4){qa_[0], qa_[1], qb_[0], qb_[1]} + gv[0] * (acc[ai][bj][m][0] * rc),
;                                 x1 = (f32x4){qc_[0], qc_[1], qd_[0], qd_[1]} + gv[1] * (acc[ai][bj][m][1] * rc);
;                     { u32x4 wx; wx.x = pk_f16(x0[0], x0[1]); wx.y = pk_f16(x0[2], x0[3]); wx.z = pk_f16(x1[0], x1[1]); wx.w = pk_f16(x1[2], x1[3]); *(u32x4*)(out + off) = wx; }
;                     ss[ai][m] += ((x0[0] * x0[0] + x0[1] * x0[1]) + (x0[2] * x0[2] + x0[3] * x0[3])) + ((x1[0] * x1[0] + x1[1] * x1[1]) + (x1[2] * x1[2] + x1[3] * x1[3]));
.LBB0_1000:
	s_lshl_b32 s5, s56, 8
	v_mov_b32_e32 v130, v222
	s_ashr_i32 s4, s57, 6
	s_or_b32 s5, s5, s21
	v_lshl_add_u32 v172, s57, 8, v223
	v_lshl_add_u32 v138, v130, 3, s5
	s_mul_hi_i32 s5, s4, 0x6000
	s_mulk_i32 s4, 0x6000
	v_ashrrev_i32_e32 v139, 31, v138
	s_add_u32 s4, s15, s4
	v_ashrrev_i32_e32 v173, 31, v172
	s_addc_u32 s5, s20, s5
	v_lshlrev_b64 v[196:197], 1, v[138:139]
	v_lshlrev_b64 v[208:209], 11, v[172:173]
	v_lshl_add_u64 v[186:187], v[138:139], 2, s[4:5]
	v_lshl_add_u64 v[138:139], s[96:97], 0, v[196:197]
	v_lshl_add_u64 v[192:193], v[138:139], 0, v[208:209]
	global_load_dwordx4 v[130:133], v[186:187], off offset:16
	global_load_dwordx4 v[134:137], v[186:187], off
	global_load_dwordx4 v[238:241], v[192:193], off
	v_or_b32_e32 v140, 16, v172
	v_ashrrev_i32_e32 v141, 31, v140
	v_lshlrev_b64 v[216:217], 11, v[140:141]
	v_lshl_add_u64 v[188:189], v[138:139], 0, v[216:217]
	global_load_dwordx4 v[242:245], v[188:189], off
	v_or_b32_e32 v140, 32, v172
	v_ashrrev_i32_e32 v141, 31, v140
	v_lshlrev_b64 v[220:221], 11, v[140:141]
	v_lshl_add_u64 v[194:195], v[138:139], 0, v[220:221]
	global_load_dwordx4 v[158:161], v[194:195], off
	v_or_b32_e32 v140, 48, v172
	v_ashrrev_i32_e32 v141, 31, v140
	v_lshlrev_b64 v[218:219], 11, v[140:141]
	v_lshl_add_u64 v[204:205], v[138:139], 0, v[218:219]
	global_load_dwordx4 v[154:157], v[204:205], off
	s_mov_b64 s[48:49], 0x40000
	v_lshl_add_u64 v[206:207], v[208:209], 0, s[48:49]
	v_lshl_add_u64 v[190:191], v[138:139], 0, v[206:207]
	global_load_dwordx4 v[150:153], v[190:191], off
	s_mov_b64 s[4:5], 0x48000
	v_lshl_add_u64 v[214:215], v[208:209], 0, s[4:5]
	v_lshl_add_u64 v[198:199], v[138:139], 0, v[214:215]
	global_load_dwordx4 v[146:149], v[198:199], off
	s_mov_b64 s[4:5], 0x50000
	v_lshl_add_u64 v[212:213], v[208:209], 0, s[4:5]
	v_lshl_add_u64 v[200:201], v[138:139], 0, v[212:213]
	global_load_dwordx4 v[142:145], v[200:201], off
	s_mov_b64 s[4:5], 0x58000
	v_lshl_add_u64 v[210:211], v[208:209], 0, s[4:5]
	v_lshl_add_u64 v[202:203], v[138:139], 0, v[210:211]
	global_load_dwordx4 v[138:141], v[202:203], off
	global_load_dword v174, v[192:193], off offset:256
	global_load_dword v174, v[188:189], off offset:256
	global_load_dword v174, v[194:195], off offset:256
	global_load_dword v174, v[204:205], off offset:256
	global_load_dword v174, v[190:191], off offset:256
	global_load_dword v174, v[198:199], off offset:256
	global_load_dword v174, v[200:201], off offset:256
	global_load_dword v174, v[202:203], off offset:256
	v_lshl_add_u64 v[208:209], s[96:97], 0, v[208:209]
	v_lshl_add_u64 v[208:209], v[208:209], 0, v[196:197]
	s_waitcnt vmcnt(0)
	v_cvt_f32_f16_e32 v174, v238
	v_cvt_f32_f16_sdwa v175, v238 dst_sel:DWORD dst_unused:UNUSED_PAD src0_sel:WORD_1
	v_cvt_f32_f16_e32 v176, v239
	v_cvt_f32_f16_sdwa v177, v239 dst_sel:DWORD dst_unused:UNUSED_PAD src0_sel:WORD_1
	v_cvt_f32_f16_e32 v238, v240
	v_cvt_f32_f16_sdwa v239, v240 dst_sel:DWORD dst_unused:UNUSED_PAD src0_sel:WORD_1
	v_cvt_f32_f16_e32 v240, v241
	v_cvt_f32_f16_sdwa v241, v241 dst_sel:DWORD dst_unused:UNUSED_PAD src0_sel:WORD_1
	v_pk_fma_f32 v[126:127], v[126:127], v[136:137], v[176:177]
	v_pk_fma_f32 v[124:125], v[124:125], v[134:135], v[174:175]
	v_pk_fma_f32 v[176:177], v[120:121], v[130:131], v[238:239]
	v_pk_fma_f32 v[174:175], v[122:123], v[132:133], v[240:241]
	v_cvt_pk_f16_f32 v120, v124, v125
	v_cvt_pk_f16_f32 v121, v126, v127
	v_cvt_pk_f16_f32 v122, v176, v177
	v_cvt_pk_f16_f32 v123, v174, v175
	global_store_dwordx4 v[208:209], v[120:123], off
	s_nop 1
	v_mul_f32_e32 v120, v125, v125
	v_mul_f32_e32 v121, v127, v127
	v_fmac_f32_e32 v120, v124, v124
	v_fmac_f32_e32 v121, v126, v126
	v_add_f32_e32 v120, v120, v121
	v_mul_f32_e32 v121, v177, v177
	v_mul_f32_e32 v122, v175, v175
	v_fmac_f32_e32 v121, v176, v176
	v_fmac_f32_e32 v122, v174, v174
	v_add_f32_e32 v121, v121, v122
	v_add_f32_e32 v237, v120, v121
	v_cvt_f32_f16_e32 v120, v242
	v_cvt_f32_f16_sdwa v121, v242 dst_sel:DWORD dst_unused:UNUSED_PAD src0_sel:WORD_1
	v_cvt_f32_f16_e32 v122, v243
	v_cvt_f32_f16_sdwa v123, v243 dst_sel:DWORD dst_unused:UNUSED_PAD src0_sel:WORD_1
	v_cvt_f32_f16_e32 v124, v244
	v_cvt_f32_f16_sdwa v125, v244 dst_sel:DWORD dst_unused:UNUSED_PAD src0_sel:WORD_1
	v_cvt_f32_f16_e32 v126, v245
	v_cvt_f32_f16_sdwa v127, v245 dst_sel:DWORD dst_unused:UNUSED_PAD src0_sel:WORD_1
	v_pk_fma_f32 v[118:119], v[118:119], v[136:137], v[122:123]
	v_pk_fma_f32 v[116:117], v[116:117], v[134:135], v[120:121]
	v_pk_fma_f32 v[112:113], v[112:113], v[130:131], v[124:125]
	v_pk_fma_f32 v[114:115], v[114:115], v[132:133], v[126:127]
	v_lshl_add_u64 v[124:125], s[96:97], 0, v[216:217]
	v_cvt_pk_f16_f32 v120, v116, v117
	v_cvt_pk_f16_f32 v121, v118, v119
	v_cvt_pk_f16_f32 v122, v112, v113
	v_cvt_pk_f16_f32 v123, v114, v115
	v_lshl_add_u64 v[216:217], v[124:125], 0, v[196:197]
	global_store_dwordx4 v[216:217], v[120:123], off
	v_cvt_f32_f16_e32 v124, v160
	v_cvt_f32_f16_sdwa v125, v160 dst_sel:DWORD dst_unused:UNUSED_PAD src0_sel:WORD_1
	v_cvt_f32_f16_e32 v120, v158
	v_cvt_f32_f16_sdwa v121, v158 dst_sel:DWORD dst_unused:UNUSED_PAD src0_sel:WORD_1
	v_cvt_f32_f16_e32 v122, v159
	v_cvt_f32_f16_sdwa v123, v159 dst_sel:DWORD dst_unused:UNUSED_PAD src0_sel:WORD_1
	v_cvt_f32_f16_e32 v126, v161
	v_cvt_f32_f16_sdwa v127, v161 dst_sel:DWORD dst_unused:UNUSED_PAD src0_sel:WORD_1
	v_pk_fma_f32 v[158:159], v[108:109], v[134:135], v[120:121]
	v_pk_fma_f32 v[110:111], v[110:111], v[136:137], v[122:123]
	v_pk_fma_f32 v[124:125], v[104:105], v[130:131], v[124:125]
	v_pk_fma_f32 v[106:107], v[106:107], v[132:133], v[126:127]
	v_lshl_add_u64 v[104:105], s[96:97], 0, v[220:221]
	v_cvt_pk_f16_f32 v120, v158, v159
; __device__ __forceinline__ unsigned pk_f16(float lo, float hi) { f32x2 v = {lo, hi}; f16x2_t h = __builtin_convertvector(v, f16x2_t); return __builtin_bit_cast(unsigned, h); }
; __device__ __forceinline__ f32x2 up_f16(unsigned w) { return __builtin_convertvector(__builtin_bit_cast(f16x2_t, w), f32x2); }
;     __device__ __forceinline__ void operator()(const f32x4 (&acc)[2][2][4][2], const Unit& u, int wr, int wc, int fr, int fq) const {
;     ...
;             for (int n = 0; n < 2; ++n) gv[n] = *(const f32x4*)(gate + (size_t)b * gstride + col0 + bj * HALF + 4 * n);
;             u32x4 pq[2][4];
; #pragma unroll
;             for (int ai = 0; ai < 2; ++ai)
; #pragma unroll
;                 for (int m = 0; m < 4; ++m) pq[ai][m] = *(const u32x4*)(base + (size_t)(row0 + ai * HALF + m * 16) * 1024 + col0 + bj * HALF);
;             asm volatile("" ::: "memory");
; #pragma unroll
;             for (int ai = 0; ai < 2; ++ai) {
; #pragma unroll
;                 for (int m = 0; m < 4; ++m) { const size_t off = (size_t)(row0 + ai * HALF + m * 16) * 1024 + col0 + bj * HALF;
;                     float rc = 1.0f; if constexpr (GN) rc = rsqrtf(gss[2 * 32768 + row0 + ai * HALF + m * 16] * (1.0f / 384.0f) + 1e-6f);
;                     const u32x4 q = pq[ai][m];
;                     const f32x2 qa_ = up_f16(q.x), qb_ = up_f16(q.y), qc_ = up_f16(q.z), qd_ = up_f16(q.w);
;                     const f32x4 x0 = (f32x4){qa_[0], qa_[1], qb_[0], qb_[1]} + gv[0] * (acc[ai][bj][m][0] * rc),
;                                 x1 = (f32x4){qc_[0], qc_[1], qd_[0], qd_[1]} + gv[1] * (acc[ai][bj][m][1] * rc);
;                     { u32x4 wx; wx.x = pk_f16(x0[0], x0[1]); wx.y = pk_f16(x0[2], x0[3]); wx.z = pk_f16(x1[0], x1[1]); wx.w = pk_f16(x1[2], x1[3]); *(u32x4*)(out + off) = wx; }
	v_cvt_pk_f16_f32 v121, v110, v111
	v_cvt_pk_f16_f32 v122, v124, v125
	v_cvt_pk_f16_f32 v123, v106, v107
	v_lshl_add_u64 v[160:161], v[104:105], 0, v[196:197]
	global_store_dwordx4 v[160:161], v[120:123], off
	v_cvt_f32_f16_e32 v104, v154
	v_cvt_f32_f16_sdwa v105, v154 dst_sel:DWORD dst_unused:UNUSED_PAD src0_sel:WORD_1
	v_cvt_f32_f16_e32 v108, v155
	v_cvt_f32_f16_sdwa v109, v155 dst_sel:DWORD dst_unused:UNUSED_PAD src0_sel:WORD_1
	v_cvt_f32_f16_e32 v120, v156
	v_cvt_f32_f16_sdwa v121, v156 dst_sel:DWORD dst_unused:UNUSED_PAD src0_sel:WORD_1
	v_cvt_f32_f16_e32 v122, v157
	v_cvt_f32_f16_sdwa v123, v157 dst_sel:DWORD dst_unused:UNUSED_PAD src0_sel:WORD_1
	v_pk_fma_f32 v[102:103], v[102:103], v[136:137], v[108:109]
	v_pk_fma_f32 v[154:155], v[100:101], v[134:135], v[104:105]
	v_pk_fma_f32 v[108:109], v[96:97], v[130:131], v[120:121]
	v_pk_fma_f32 v[98:99], v[98:99], v[132:133], v[122:123]
	v_lshl_add_u64 v[96:97], s[96:97], 0, v[218:219]
	v_cvt_pk_f16_f32 v120, v154, v155
	v_cvt_pk_f16_f32 v121, v102, v103
	v_cvt_pk_f16_f32 v122, v108, v109
	v_cvt_pk_f16_f32 v123, v98, v99
	v_lshl_add_u64 v[156:157], v[96:97], 0, v[196:197]
	global_store_dwordx4 v[156:157], v[120:123], off
	v_cvt_f32_f16_e32 v96, v150
	v_cvt_f32_f16_sdwa v97, v150 dst_sel:DWORD dst_unused:UNUSED_PAD src0_sel:WORD_1
	v_cvt_f32_f16_e32 v100, v151
	v_cvt_f32_f16_sdwa v101, v151 dst_sel:DWORD dst_unused:UNUSED_PAD src0_sel:WORD_1
	v_cvt_f32_f16_e32 v104, v152
	v_cvt_f32_f16_sdwa v105, v152 dst_sel:DWORD dst_unused:UNUSED_PAD src0_sel:WORD_1
	v_cvt_f32_f16_e32 v120, v153
	v_cvt_f32_f16_sdwa v121, v153 dst_sel:DWORD dst_unused:UNUSED_PAD src0_sel:WORD_1
	v_pk_fma_f32 v[100:101], v[94:95], v[136:137], v[100:101]
	v_pk_fma_f32 v[150:151], v[92:93], v[134:135], v[96:97]
	v_cvt_pk_f16_f32 v93, v100, v101
	v_pk_fma_f32 v[90:91], v[90:91], v[132:133], v[120:121]
	v_pk_fma_f32 v[120:121], v[88:89], v[130:131], v[104:105]
	v_lshl_add_u64 v[88:89], s[96:97], 0, v[206:207]
	v_cvt_pk_f16_f32 v92, v150, v151
	v_cvt_pk_f16_f32 v94, v120, v121
	v_cvt_pk_f16_f32 v95, v90, v91
	v_lshl_add_u64 v[152:153], v[88:89], 0, v[196:197]
	global_store_dwordx4 v[152:153], v[92:95], off
	v_cvt_f32_f16_e32 v88, v146
	v_cvt_f32_f16_sdwa v89, v146 dst_sel:DWORD dst_unused:UNUSED_PAD src0_sel:WORD_1
	v_cvt_f32_f16_e32 v92, v147
	v_cvt_f32_f16_sdwa v93, v147 dst_sel:DWORD dst_unused:UNUSED_PAD src0_sel:WORD_1
	v_cvt_f32_f16_e32 v96, v148
	v_cvt_f32_f16_sdwa v97, v148 dst_sel:DWORD dst_unused:UNUSED_PAD src0_sel:WORD_1
	v_cvt_f32_f16_e32 v104, v149
	v_cvt_f32_f16_sdwa v105, v149 dst_sel:DWORD dst_unused:UNUSED_PAD src0_sel:WORD_1
	v_pk_fma_f32 v[94:95], v[86:87], v[136:137], v[92:93]
	v_pk_fma_f32 v[146:147], v[84:85], v[134:135], v[88:89]
	v_lshl_add_u64 v[86:87], s[96:97], 0, v[214:215]
	v_pk_fma_f32 v[84:85], v[82:83], v[132:133], v[104:105]
	v_pk_fma_f32 v[104:105], v[80:81], v[130:131], v[96:97]
	v_cvt_pk_f16_f32 v80, v146, v147
	v_cvt_pk_f16_f32 v81, v94, v95
	v_cvt_pk_f16_f32 v82, v104, v105
	v_cvt_pk_f16_f32 v83, v84, v85
	v_lshl_add_u64 v[148:149], v[86:87], 0, v[196:197]
	global_store_dwordx4 v[148:149], v[80:83], off
	v_cvt_f32_f16_e32 v86, v144
	v_cvt_f32_f16_sdwa v87, v144 dst_sel:DWORD dst_unused:UNUSED_PAD src0_sel:WORD_1
	v_cvt_f32_f16_e32 v80, v142
	v_cvt_f32_f16_sdwa v81, v142 dst_sel:DWORD dst_unused:UNUSED_PAD src0_sel:WORD_1
	v_cvt_f32_f16_e32 v82, v143
	v_cvt_f32_f16_sdwa v83, v143 dst_sel:DWORD dst_unused:UNUSED_PAD src0_sel:WORD_1
	v_cvt_f32_f16_e32 v92, v145
	v_cvt_f32_f16_sdwa v93, v145 dst_sel:DWORD dst_unused:UNUSED_PAD src0_sel:WORD_1
	v_pk_fma_f32 v[126:127], v[76:77], v[134:135], v[80:81]
	v_pk_fma_f32 v[88:89], v[78:79], v[136:137], v[82:83]
	v_pk_fma_f32 v[96:97], v[72:73], v[130:131], v[86:87]
	v_pk_fma_f32 v[82:83], v[74:75], v[132:133], v[92:93]
	v_lshl_add_u64 v[76:77], s[96:97], 0, v[212:213]
	v_cvt_pk_f16_f32 v72, v126, v127
	v_cvt_pk_f16_f32 v73, v88, v89
	v_cvt_pk_f16_f32 v74, v96, v97
	v_cvt_pk_f16_f32 v75, v82, v83
	v_lshl_add_u64 v[142:143], v[76:77], 0, v[196:197]
	global_store_dwordx4 v[142:143], v[72:75], off
	v_cvt_f32_f16_e32 v76, v140
	v_cvt_f32_f16_sdwa v77, v140 dst_sel:DWORD dst_unused:UNUSED_PAD src0_sel:WORD_1
	v_cvt_f32_f16_e32 v72, v138
	v_cvt_f32_f16_sdwa v73, v138 dst_sel:DWORD dst_unused:UNUSED_PAD src0_sel:WORD_1
	v_cvt_f32_f16_e32 v74, v139
	v_cvt_f32_f16_sdwa v75, v139 dst_sel:DWORD dst_unused:UNUSED_PAD src0_sel:WORD_1
	v_cvt_f32_f16_e32 v78, v141
	v_cvt_f32_f16_sdwa v79, v141 dst_sel:DWORD dst_unused:UNUSED_PAD src0_sel:WORD_1
	v_pk_fma_f32 v[122:123], v[68:69], v[134:135], v[72:73]
	v_pk_fma_f32 v[86:87], v[70:71], v[136:137], v[74:75]
	v_pk_fma_f32 v[92:93], v[64:65], v[130:131], v[76:77]
	v_pk_fma_f32 v[80:81], v[66:67], v[132:133], v[78:79]
	v_lshl_add_u64 v[68:69], s[96:97], 0, v[210:211]
	v_cvt_pk_f16_f32 v64, v122, v123
	v_cvt_pk_f16_f32 v65, v86, v87
	v_cvt_pk_f16_f32 v66, v92, v93
	v_cvt_pk_f16_f32 v67, v80, v81
	v_lshl_add_u64 v[130:131], v[68:69], 0, v[196:197]
	global_store_dwordx4 v[130:131], v[64:67], off
	global_load_dwordx4 v[64:67], v[186:187], off offset:528
	global_load_dwordx4 v[68:71], v[186:187], off offset:512
	global_load_dwordx4 v[132:135], v[192:193], off offset:256
	global_load_dwordx4 v[136:139], v[188:189], off offset:256
	s_nop 0
	global_load_dwordx4 v[186:189], v[194:195], off offset:256
	s_nop 0
	global_load_dwordx4 v[192:195], v[204:205], off offset:256
	s_nop 0
	global_load_dwordx4 v[204:207], v[190:191], off offset:256
	s_nop 0
	global_load_dwordx4 v[196:199], v[198:199], off offset:256
	s_nop 0
	global_load_dwordx4 v[76:79], v[200:201], off offset:256
	global_load_dwordx4 v[72:75], v[202:203], off offset:256
	s_waitcnt vmcnt(7)
; __device__ __forceinline__ unsigned pk_f16(float lo, float hi) { f32x2 v = {lo, hi}; f16x2_t h = __builtin_convertvector(v, f16x2_t); return __builtin_bit_cast(unsigned, h); }
; __device__ __forceinline__ f32x2 up_f16(unsigned w) { return __builtin_convertvector(__builtin_bit_cast(f16x2_t, w), f32x2); }
;     __device__ __forceinline__ void operator()(const f32x4 (&acc)[2][2][4][2], const Unit& u, int wr, int wc, int fr, int fq) const {
;     ...
;             for (int ai = 0; ai < 2; ++ai) {
; #pragma unroll
;                 for (int m = 0; m < 4; ++m) { const size_t off = (size_t)(row0 + ai * HALF + m * 16) * 1024 + col0 + bj * HALF;
;                     float rc = 1.0f; if constexpr (GN) rc = rsqrtf(gss[2 * 32768 + row0 + ai * HALF + m * 16] * (1.0f / 384.0f) + 1e-6f);
;                     const u32x4 q = pq[ai][m];
;                     const f32x2 qa_ = up_f16(q.x), qb_ = up_f16(q.y), qc_ = up_f16(q.z), qd_ = up_f16(q.w);
;                     const f32x4 x0 = (f32x4){qa_[0], qa_[1], qb_[0], qb_[1]} + gv[0] * (acc[ai][bj][m][0] * rc),
;                                 x1 = (f32x4){qc_[0], qc_[1], qd_[0], qd_[1]} + gv[1] * (acc[ai][bj][m][1] * rc);
;                     { u32x4 wx; wx.x = pk_f16(x0[0], x0[1]); wx.y = pk_f16(x0[2], x0[3]); wx.z = pk_f16(x1[0], x1[1]); wx.w = pk_f16(x1[2], x1[3]); *(u32x4*)(out + off) = wx; }
;                     ss[ai][m] += ((x0[0] * x0[0] + x0[1] * x0[1]) + (x0[2] * x0[2] + x0[3] * x0[3])) + ((x1[0] * x1[0] + x1[1] * x1[1]) + (x1[2] * x1[2] + x1[3] * x1[3]));
	v_cvt_f32_f16_e32 v140, v132
	v_cvt_f32_f16_sdwa v141, v132 dst_sel:DWORD dst_unused:UNUSED_PAD src0_sel:WORD_1
	v_cvt_f32_f16_e32 v132, v133
	v_cvt_f32_f16_sdwa v133, v133 dst_sel:DWORD dst_unused:UNUSED_PAD src0_sel:WORD_1
	v_cvt_f32_f16_e32 v144, v134
	v_cvt_f32_f16_sdwa v145, v134 dst_sel:DWORD dst_unused:UNUSED_PAD src0_sel:WORD_1
	v_cvt_f32_f16_e32 v134, v135
	v_cvt_f32_f16_sdwa v135, v135 dst_sel:DWORD dst_unused:UNUSED_PAD src0_sel:WORD_1
	v_pk_fma_f32 v[62:63], v[62:63], v[70:71], v[132:133]
	v_pk_fma_f32 v[60:61], v[60:61], v[68:69], v[140:141]
	v_pk_fma_f32 v[132:133], v[58:59], v[66:67], v[134:135]
	v_pk_fma_f32 v[134:135], v[56:57], v[64:65], v[144:145]
	v_cvt_pk_f16_f32 v56, v60, v61
	v_cvt_pk_f16_f32 v57, v62, v63
	v_cvt_pk_f16_f32 v58, v134, v135
	v_cvt_pk_f16_f32 v59, v132, v133
	global_store_dwordx4 v[208:209], v[56:59], off offset:256
	s_nop 1
	v_mul_f32_e32 v56, v61, v61
	v_mul_f32_e32 v57, v63, v63
	v_fmac_f32_e32 v56, v60, v60
	v_fmac_f32_e32 v57, v62, v62
	v_add_f32_e32 v56, v56, v57
	v_mul_f32_e32 v57, v135, v135
	v_mul_f32_e32 v58, v133, v133
	v_fmac_f32_e32 v57, v134, v134
	v_fmac_f32_e32 v58, v132, v132
	v_add_f32_e32 v57, v57, v58
	v_add_f32_e32 v56, v56, v57
	v_add_f32_e32 v132, v237, v56
	s_waitcnt vmcnt(7)
	v_cvt_f32_f16_e32 v56, v136
	v_cvt_f32_f16_sdwa v57, v136 dst_sel:DWORD dst_unused:UNUSED_PAD src0_sel:WORD_1
	v_cvt_f32_f16_e32 v58, v137
	v_cvt_f32_f16_sdwa v59, v137 dst_sel:DWORD dst_unused:UNUSED_PAD src0_sel:WORD_1
	v_cvt_f32_f16_e32 v60, v138
	v_cvt_f32_f16_sdwa v61, v138 dst_sel:DWORD dst_unused:UNUSED_PAD src0_sel:WORD_1
	v_cvt_f32_f16_e32 v62, v139
	v_cvt_f32_f16_sdwa v63, v139 dst_sel:DWORD dst_unused:UNUSED_PAD src0_sel:WORD_1
	v_pk_fma_f32 v[54:55], v[54:55], v[70:71], v[58:59]
	v_pk_fma_f32 v[52:53], v[52:53], v[68:69], v[56:57]
	v_pk_fma_f32 v[48:49], v[48:49], v[64:65], v[60:61]
	v_pk_fma_f32 v[50:51], v[50:51], v[66:67], v[62:63]
	v_cvt_pk_f16_f32 v56, v52, v53
	v_cvt_pk_f16_f32 v57, v54, v55
	v_cvt_pk_f16_f32 v58, v48, v49
	v_cvt_pk_f16_f32 v59, v50, v51
	global_store_dwordx4 v[216:217], v[56:59], off offset:256
	s_waitcnt vmcnt(7)
	v_cvt_f32_f16_e32 v60, v188
	v_cvt_f32_f16_sdwa v61, v188 dst_sel:DWORD dst_unused:UNUSED_PAD src0_sel:WORD_1
	v_cvt_f32_f16_e32 v56, v186
	v_cvt_f32_f16_sdwa v57, v186 dst_sel:DWORD dst_unused:UNUSED_PAD src0_sel:WORD_1
	v_cvt_f32_f16_e32 v58, v187
	v_cvt_f32_f16_sdwa v59, v187 dst_sel:DWORD dst_unused:UNUSED_PAD src0_sel:WORD_1
	v_cvt_f32_f16_e32 v62, v189
	v_cvt_f32_f16_sdwa v63, v189 dst_sel:DWORD dst_unused:UNUSED_PAD src0_sel:WORD_1
	v_pk_fma_f32 v[44:45], v[44:45], v[68:69], v[56:57]
	v_pk_fma_f32 v[46:47], v[46:47], v[70:71], v[58:59]
	v_pk_fma_f32 v[40:41], v[40:41], v[64:65], v[60:61]
	v_pk_fma_f32 v[42:43], v[42:43], v[66:67], v[62:63]
	v_cvt_pk_f16_f32 v56, v44, v45
	v_cvt_pk_f16_f32 v57, v46, v47
	v_cvt_pk_f16_f32 v58, v40, v41
	v_cvt_pk_f16_f32 v59, v42, v43
	global_store_dwordx4 v[160:161], v[56:59], off offset:256
	s_waitcnt vmcnt(7)
	v_cvt_f32_f16_e32 v60, v194
	v_cvt_f32_f16_sdwa v61, v194 dst_sel:DWORD dst_unused:UNUSED_PAD src0_sel:WORD_1
	v_cvt_f32_f16_e32 v56, v192
	v_cvt_f32_f16_sdwa v57, v192 dst_sel:DWORD dst_unused:UNUSED_PAD src0_sel:WORD_1
	v_cvt_f32_f16_e32 v58, v193
	v_cvt_f32_f16_sdwa v59, v193 dst_sel:DWORD dst_unused:UNUSED_PAD src0_sel:WORD_1
	v_cvt_f32_f16_e32 v62, v195
	v_cvt_f32_f16_sdwa v63, v195 dst_sel:DWORD dst_unused:UNUSED_PAD src0_sel:WORD_1
	v_pk_fma_f32 v[36:37], v[36:37], v[68:69], v[56:57]
	v_pk_fma_f32 v[38:39], v[38:39], v[70:71], v[58:59]
	v_pk_fma_f32 v[32:33], v[32:33], v[64:65], v[60:61]
	v_pk_fma_f32 v[34:35], v[34:35], v[66:67], v[62:63]
	v_cvt_pk_f16_f32 v56, v36, v37
	v_cvt_pk_f16_f32 v57, v38, v39
	v_cvt_pk_f16_f32 v58, v32, v33
	v_cvt_pk_f16_f32 v59, v34, v35
	global_store_dwordx4 v[156:157], v[56:59], off offset:256
	s_waitcnt vmcnt(7)
; __device__ __forceinline__ unsigned pk_f16(float lo, float hi) { f32x2 v = {lo, hi}; f16x2_t h = __builtin_convertvector(v, f16x2_t); return __builtin_bit_cast(unsigned, h); }
; __device__ __forceinline__ f32x2 up_f16(unsigned w) { return __builtin_convertvector(__builtin_bit_cast(f16x2_t, w), f32x2); }
;     __device__ __forceinline__ void operator()(const f32x4 (&acc)[2][2][4][2], const Unit& u, int wr, int wc, int fr, int fq) const {
;     ...
;             for (int ai = 0; ai < 2; ++ai) {
; #pragma unroll
;                 for (int m = 0; m < 4; ++m) { const size_t off = (size_t)(row0 + ai * HALF + m * 16) * 1024 + col0 + bj * HALF;
;                     float rc = 1.0f; if constexpr (GN) rc = rsqrtf(gss[2 * 32768 + row0 + ai * HALF + m * 16] * (1.0f / 384.0f) + 1e-6f);
;                     const u32x4 q = pq[ai][m];
;                     const f32x2 qa_ = up_f16(q.x), qb_ = up_f16(q.y), qc_ = up_f16(q.z), qd_ = up_f16(q.w);
;                     const f32x4 x0 = (f32x4){qa_[0], qa_[1], qb_[0], qb_[1]} + gv[0] * (acc[ai][bj][m][0] * rc),
;                                 x1 = (f32x4){qc_[0], qc_[1], qd_[0], qd_[1]} + gv[1] * (acc[ai][bj][m][1] * rc);
;                     { u32x4 wx; wx.x = pk_f16(x0[0], x0[1]); wx.y = pk_f16(x0[2], x0[3]); wx.z = pk_f16(x1[0], x1[1]); wx.w = pk_f16(x1[2], x1[3]); *(u32x4*)(out + off) = wx; }
;                     ss[ai][m] += ((x0[0] * x0[0] + x0[1] * x0[1]) + (x0[2] * x0[2] + x0[3] * x0[3])) + ((x1[0] * x1[0] + x1[1] * x1[1]) + (x1[2] * x1[2] + x1[3] * x1[3]));
;                 }
;                 asm volatile("" ::: "memory");
;             }
;         }
; #pragma unroll
;         for (int ai = 0; ai < 2; ++ai)
; #pragma unroll
;             for (int m = 0; m < 4; ++m) { float t = ss[ai][m]; t += __shfl_xor(t, 16); t += __shfl_xor(t, 32);
;                 if (fq == 0) atomicAdd(rowss + row0 + ai * HALF + m * 16, t); }
	v_cvt_f32_f16_e32 v60, v206
	v_cvt_f32_f16_sdwa v61, v206 dst_sel:DWORD dst_unused:UNUSED_PAD src0_sel:WORD_1
	v_cvt_f32_f16_e32 v56, v204
	v_cvt_f32_f16_sdwa v57, v204 dst_sel:DWORD dst_unused:UNUSED_PAD src0_sel:WORD_1
	v_cvt_f32_f16_e32 v58, v205
	v_cvt_f32_f16_sdwa v59, v205 dst_sel:DWORD dst_unused:UNUSED_PAD src0_sel:WORD_1
	v_cvt_f32_f16_e32 v62, v207
	v_cvt_f32_f16_sdwa v63, v207 dst_sel:DWORD dst_unused:UNUSED_PAD src0_sel:WORD_1
	v_pk_fma_f32 v[28:29], v[28:29], v[68:69], v[56:57]
	v_pk_fma_f32 v[30:31], v[30:31], v[70:71], v[58:59]
	v_pk_fma_f32 v[24:25], v[24:25], v[64:65], v[60:61]
	v_pk_fma_f32 v[26:27], v[26:27], v[66:67], v[62:63]
	v_cvt_pk_f16_f32 v56, v28, v29
	v_cvt_pk_f16_f32 v57, v30, v31
	v_cvt_pk_f16_f32 v58, v24, v25
	v_cvt_pk_f16_f32 v59, v26, v27
	global_store_dwordx4 v[152:153], v[56:59], off offset:256
	s_waitcnt vmcnt(7)
	v_cvt_f32_f16_e32 v60, v198
	v_cvt_f32_f16_sdwa v61, v198 dst_sel:DWORD dst_unused:UNUSED_PAD src0_sel:WORD_1
	v_cvt_f32_f16_e32 v56, v196
	v_cvt_f32_f16_sdwa v57, v196 dst_sel:DWORD dst_unused:UNUSED_PAD src0_sel:WORD_1
	v_cvt_f32_f16_e32 v58, v197
	v_cvt_f32_f16_sdwa v59, v197 dst_sel:DWORD dst_unused:UNUSED_PAD src0_sel:WORD_1
	v_cvt_f32_f16_e32 v62, v199
	v_cvt_f32_f16_sdwa v63, v199 dst_sel:DWORD dst_unused:UNUSED_PAD src0_sel:WORD_1
	v_pk_fma_f32 v[20:21], v[20:21], v[68:69], v[56:57]
	v_pk_fma_f32 v[22:23], v[22:23], v[70:71], v[58:59]
	v_pk_fma_f32 v[16:17], v[16:17], v[64:65], v[60:61]
	v_pk_fma_f32 v[18:19], v[18:19], v[66:67], v[62:63]
	v_cvt_pk_f16_f32 v56, v20, v21
	v_cvt_pk_f16_f32 v57, v22, v23
	v_cvt_pk_f16_f32 v58, v16, v17
	v_cvt_pk_f16_f32 v59, v18, v19
	global_store_dwordx4 v[148:149], v[56:59], off offset:256
	s_waitcnt vmcnt(7)
	v_cvt_f32_f16_e32 v60, v78
	v_cvt_f32_f16_sdwa v61, v78 dst_sel:DWORD dst_unused:UNUSED_PAD src0_sel:WORD_1
	v_cvt_f32_f16_e32 v56, v76
	v_cvt_f32_f16_sdwa v57, v76 dst_sel:DWORD dst_unused:UNUSED_PAD src0_sel:WORD_1
	v_cvt_f32_f16_e32 v58, v77
	v_cvt_f32_f16_sdwa v59, v77 dst_sel:DWORD dst_unused:UNUSED_PAD src0_sel:WORD_1
	v_cvt_f32_f16_e32 v62, v79
	v_cvt_f32_f16_sdwa v63, v79 dst_sel:DWORD dst_unused:UNUSED_PAD src0_sel:WORD_1
	v_pk_fma_f32 v[12:13], v[12:13], v[68:69], v[56:57]
	v_pk_fma_f32 v[14:15], v[14:15], v[70:71], v[58:59]
	v_pk_fma_f32 v[8:9], v[8:9], v[64:65], v[60:61]
	v_pk_fma_f32 v[10:11], v[10:11], v[66:67], v[62:63]
	v_cvt_pk_f16_f32 v56, v12, v13
	v_cvt_pk_f16_f32 v57, v14, v15
	v_cvt_pk_f16_f32 v58, v8, v9
	v_cvt_pk_f16_f32 v59, v10, v11
	global_store_dwordx4 v[142:143], v[56:59], off offset:256
	s_waitcnt vmcnt(7)
	v_cvt_f32_f16_e32 v60, v74
	v_cvt_f32_f16_sdwa v61, v74 dst_sel:DWORD dst_unused:UNUSED_PAD src0_sel:WORD_1
	v_cvt_f32_f16_e32 v56, v72
	v_cvt_f32_f16_sdwa v57, v72 dst_sel:DWORD dst_unused:UNUSED_PAD src0_sel:WORD_1
	v_cvt_f32_f16_e32 v58, v73
	v_cvt_f32_f16_sdwa v59, v73 dst_sel:DWORD dst_unused:UNUSED_PAD src0_sel:WORD_1
	v_cvt_f32_f16_e32 v62, v75
	v_cvt_f32_f16_sdwa v63, v75 dst_sel:DWORD dst_unused:UNUSED_PAD src0_sel:WORD_1
	v_pk_fma_f32 v[4:5], v[4:5], v[68:69], v[56:57]
	v_pk_fma_f32 v[6:7], v[6:7], v[70:71], v[58:59]
	v_pk_fma_f32 v[0:1], v[0:1], v[64:65], v[60:61]
	v_pk_fma_f32 v[2:3], v[2:3], v[66:67], v[62:63]
	v_cvt_pk_f16_f32 v56, v4, v5
	v_cvt_pk_f16_f32 v57, v6, v7
	v_cvt_pk_f16_f32 v58, v0, v1
	v_cvt_pk_f16_f32 v59, v2, v3
	global_store_dwordx4 v[130:131], v[56:59], off offset:256
	s_nop 1
	v_and_b32_e32 v57, 64, v230
	v_xor_b32_e32 v56, 16, v230
	v_add_u32_e32 v57, 64, v57
	v_cmp_lt_i32_e32 vcc, v56, v57
	s_nop 1
	v_cndmask_b32_e32 v56, v230, v56, vcc
	v_lshlrev_b32_e32 v58, 2, v56
	v_xor_b32_e32 v56, 32, v230
	v_cmp_lt_i32_e32 vcc, v56, v57
	s_nop 1
	v_cndmask_b32_e32 v56, v230, v56, vcc
	v_lshlrev_b32_e32 v59, 2, v56
	ds_bpermute_b32 v56, v58, v132
	s_waitcnt lgkmcnt(0)
	v_add_f32_e32 v60, v132, v56
	ds_bpermute_b32 v61, v59, v60
	v_lshl_add_u64 v[56:57], v[172:173], 2, s[12:13]
	s_and_saveexec_b64 s[4:5], s[38:39]
	s_cbranch_execz .LBB0_1002
	s_waitcnt lgkmcnt(0)
	v_add_f32_e32 v60, v60, v61
	global_atomic_add_f32 v[56:57], v60, off
